# speedup vs baseline: 1.1554x; 1.0019x over previous
.LBB0_693:
	s_andn2_b64 vcc, exec, s[52:53]
	s_cbranch_vccnz .LBB0_266
	s_barrier
	s_setprio 3
	s_and_saveexec_b64 s[18:19], s[46:47]
	s_cbranch_execz .LBB0_713
	s_mov_b32 s0, 1
	s_mov_b32 s6, 0
	s_mov_b32 s7, 32

.LBB0_726:
	s_or_b64 exec, exec, s[6:7]
	s_ashr_i32 s0, s21, 6
	s_sub_i32 s2, 31, s0
	s_add_i32 s6, s0, -16
	s_cmp_lt_i32 s0, 16
	s_cselect_b32 s38, s2, s6
	s_lshl_b32 s0, s21, 9
	s_and_b32 s22, s0, 0x2000
	s_and_b32 s8, s21, 15
	s_mul_i32 s0, s22, 0x1800
	s_add_u32 s6, s18, s0
	s_addc_u32 s7, s19, 0
	s_waitcnt lgkmcnt(0)
	s_barrier
	s_setprio 0
	s_and_saveexec_b64 s[10:11], s[48:49]
	s_xor_b64 s[10:11], exec, s[10:11]
	s_lshl_b32 s2, s8, 6
	s_or_saveexec_b64 s[10:11], s[10:11]
	s_bfe_u32 s0, s21, 0x10005
	s_lshl_b32 s9, s38, 8
	s_lshl_b32 s12, s0, 7
	s_or_b32 s23, s9, s12
	v_mov_b64_e32 v[118:119], s[2:3]
	s_xor_b64 exec, exec, s[10:11]
	s_cbranch_execz .LBB0_741
	s_lshl_b32 s2, s8, 6
	s_cmp_lt_i32 s38, 1
	s_cbranch_scc1 .LBB0_739
	v_add_u32_e32 v4, s23, v98
	v_mov_b64_e32 v[2:3], s[6:7]
	v_mad_i64_i32 v[2:3], s[8:9], v4, s39, v[2:3]
	s_lshl_b32 s8, s2, 1
	s_mov_b32 s9, s3
	s_waitcnt vmcnt(9)
	v_lshl_add_u64 v[14:15], v[2:3], 0, s[8:9]
	global_load_dwordx4 v[2:5], v[14:15], off
	global_load_dwordx4 v[6:9], v[14:15], off offset:16
	global_load_dwordx4 v[10:13], v[14:15], off offset:32
	global_load_dwordx4 v[18:21], v[14:15], off offset:48
	global_load_dwordx4 v[26:29], v[14:15], off offset:64
	global_load_dwordx4 v[34:37], v[14:15], off offset:80
	global_load_dwordx4 v[42:45], v[14:15], off offset:96
	global_load_dwordx4 v[70:73], v[14:15], off offset:112
	s_mov_b32 s8, 0
	v_mov_b32_e32 v68, -1
	v_mov_b32_e32 v62, 0xff61b1e6
	s_mov_b32 s9, 0x9000
	v_mov_b32_e32 v64, 0xff61b1e6
	v_mov_b32_e32 v69, -1
	s_waitcnt vmcnt(7)
	v_lshlrev_b32_e32 v50, 16, v2
	v_and_b32_e32 v51, 0xffff0000, v2
	v_lshlrev_b32_e32 v52, 16, v3
	v_and_b32_e32 v53, 0xffff0000, v3
	v_lshlrev_b32_e32 v54, 16, v4
	v_and_b32_e32 v55, 0xffff0000, v4
	v_lshlrev_b32_e32 v56, 16, v5
	v_and_b32_e32 v57, 0xffff0000, v5
	s_waitcnt vmcnt(6)
	v_lshlrev_b32_e32 v58, 16, v6
	v_and_b32_e32 v59, 0xffff0000, v6
	v_lshlrev_b32_e32 v60, 16, v7
	v_and_b32_e32 v61, 0xffff0000, v7
	v_lshlrev_b32_e32 v63, 16, v8
	v_and_b32_e32 v65, 0xffff0000, v8
	v_lshlrev_b32_e32 v66, 16, v9
	v_and_b32_e32 v67, 0xffff0000, v9
	s_waitcnt vmcnt(5)
	v_lshlrev_b32_e32 v3, 16, v12
	v_lshlrev_b32_e32 v2, 16, v10
	v_and_b32_e32 v5, 0xffff0000, v12
	v_and_b32_e32 v4, 0xffff0000, v10
	v_lshlrev_b32_e32 v7, 16, v13
	v_lshlrev_b32_e32 v6, 16, v11
	v_and_b32_e32 v9, 0xffff0000, v13
	v_and_b32_e32 v8, 0xffff0000, v11
	s_waitcnt vmcnt(4)
	v_lshlrev_b32_e32 v11, 16, v20
	v_lshlrev_b32_e32 v10, 16, v18
	v_and_b32_e32 v13, 0xffff0000, v20
	v_and_b32_e32 v12, 0xffff0000, v18
	v_lshlrev_b32_e32 v15, 16, v21
	v_lshlrev_b32_e32 v14, 16, v19
	v_and_b32_e32 v17, 0xffff0000, v21
	v_and_b32_e32 v16, 0xffff0000, v19
	s_waitcnt vmcnt(3)
	v_lshlrev_b32_e32 v19, 16, v28
	v_lshlrev_b32_e32 v18, 16, v26
	v_and_b32_e32 v21, 0xffff0000, v28
	v_and_b32_e32 v20, 0xffff0000, v26
	v_lshlrev_b32_e32 v23, 16, v29
	v_lshlrev_b32_e32 v22, 16, v27
	v_and_b32_e32 v25, 0xffff0000, v29
	v_and_b32_e32 v24, 0xffff0000, v27
	s_waitcnt vmcnt(2)
	v_lshlrev_b32_e32 v27, 16, v36
	v_lshlrev_b32_e32 v26, 16, v34
	v_and_b32_e32 v29, 0xffff0000, v36
	v_and_b32_e32 v28, 0xffff0000, v34
	v_lshlrev_b32_e32 v31, 16, v37
	v_lshlrev_b32_e32 v30, 16, v35
	v_and_b32_e32 v33, 0xffff0000, v37
	v_and_b32_e32 v32, 0xffff0000, v35
	s_waitcnt vmcnt(1)
	v_lshlrev_b32_e32 v35, 16, v44
	v_lshlrev_b32_e32 v34, 16, v42
	v_and_b32_e32 v37, 0xffff0000, v44
	v_and_b32_e32 v36, 0xffff0000, v42
	v_lshlrev_b32_e32 v39, 16, v45
	v_lshlrev_b32_e32 v38, 16, v43
	v_and_b32_e32 v41, 0xffff0000, v45
	v_and_b32_e32 v40, 0xffff0000, v43
	s_waitcnt vmcnt(0)
	v_lshlrev_b32_e32 v43, 16, v72
	v_lshlrev_b32_e32 v42, 16, v70
	v_and_b32_e32 v45, 0xffff0000, v72
	v_and_b32_e32 v44, 0xffff0000, v70
	v_lshlrev_b32_e32 v47, 16, v73
	v_lshlrev_b32_e32 v46, 16, v71
	v_and_b32_e32 v49, 0xffff0000, v73
	v_and_b32_e32 v48, 0xffff0000, v71
	v_mov_b32_e32 v71, 0xff61b1e6
	v_mov_b32_e32 v70, -1
